# Win epilogue NA q/k path: all four gain-vector loads issued together (one exposed latency instead of two), stacked on v138
# baseline (speedup 1.0000x reference)
.LBB0_267:
	s_and_b64 vcc, exec, s[0:1]
	s_cbranch_vccz .LBB0_269
	s_cmp_lt_i32 s16, 2
	s_cselect_b64 vcc, -1, 0
	s_and_b64 s[0:1], vcc, exec
	v_readlane_b32 s44, v251, 49
	v_readlane_b32 s0, v254, 63
	v_readlane_b32 s45, v251, 50
	v_readlane_b32 s46, v251, 51
	v_readlane_b32 s47, v251, 52
	v_readlane_b32 s1, v255, 0
	s_cselect_b32 s9, s45, s47
	s_cselect_b32 s11, s44, s46
	s_lshl_b64 s[0:1], s[0:1], 2
	s_add_u32 s0, s11, s0
	s_addc_u32 s1, s9, s1
	v_ashrrev_i32_e32 v153, 31, v152
	v_mov_b32_e32 v128, 0x3e38aa3b
	v_lshl_add_u64 v[136:137], v[152:153], 2, s[0:1]
	v_cndmask_b32_e32 v158, 1.0, v128, vcc
	global_load_dwordx4 v[152:155], v[136:137], off offset:16
	global_load_dwordx4 v[128:131], v[136:137], off
	global_load_dwordx4 v[164:167], v[136:137], off offset:144
	global_load_dwordx4 v[168:171], v[136:137], off offset:128
	v_pk_mul_f32 v[162:163], v[124:125], v[124:125]
	v_readlane_b32 s0, v252, 52
	v_readlane_b32 s1, v252, 53
	v_ashrrev_i32_e32 v151, 31, v150
	v_readlane_b32 s48, v251, 53
	v_readlane_b32 s49, v251, 54
	v_readlane_b32 s50, v251, 55
	v_readlane_b32 s51, v251, 56
	v_readlane_b32 s52, v251, 57
	v_readlane_b32 s53, v251, 58
	v_readlane_b32 s54, v251, 59
	v_readlane_b32 s55, v251, 60
	v_readlane_b32 s56, v251, 61
	v_readlane_b32 s57, v251, 62
	v_readlane_b32 s58, v251, 63
	v_readlane_b32 s59, v252, 0
	s_waitcnt vmcnt(2)
	v_pk_mul_f32 v[132:133], v[158:159], v[130:131] op_sel_hi:[0,1]
	v_pk_mul_f32 v[134:135], v[158:159], v[128:129] op_sel_hi:[0,1]
	v_pk_mul_f32 v[128:129], v[158:159], v[154:155] op_sel_hi:[0,1]
	v_pk_mul_f32 v[130:131], v[158:159], v[152:153] op_sel_hi:[0,1]
	s_waitcnt vmcnt(0)
	v_mov_b32_e32 v174, v164
	v_mov_b32_e32 v175, v165
	v_mov_b32_e32 v176, v166
	v_mov_b32_e32 v177, v167
	v_mov_b32_e32 v152, v168
	v_mov_b32_e32 v153, v169
	v_mov_b32_e32 v154, v170
	v_mov_b32_e32 v155, v171
	s_waitcnt vmcnt(1)
	v_pk_mul_f32 v[136:137], v[158:159], v[176:177] op_sel_hi:[0,1]
	s_waitcnt vmcnt(0)
	v_pk_mul_f32 v[154:155], v[158:159], v[154:155] op_sel_hi:[0,1]
	v_pk_mul_f32 v[156:157], v[158:159], v[152:153] op_sel_hi:[0,1]
	v_pk_mul_f32 v[152:153], v[158:159], v[174:175] op_sel_hi:[0,1]
	v_pk_mul_f32 v[158:159], v[126:127], v[126:127]
	v_lshlrev_b64 v[174:175], 1, v[150:151]
	v_pk_mov_b32 v[164:165], v[162:163], v[158:159] op_sel:[1,0]
	v_mov_b32_e32 v163, v159
	v_pk_add_f32 v[158:159], v[164:165], v[162:163]
	v_pk_mul_f32 v[162:163], v[122:123], v[122:123]
	v_pk_mul_f32 v[164:165], v[120:121], v[120:121]
	v_pk_add_f32 v[158:159], v[158:159], v[158:159] op_sel:[0,1] op_sel_hi:[1,0]
	v_pk_mov_b32 v[166:167], v[164:165], v[162:163] op_sel:[1,0]
	v_mov_b32_e32 v165, v163
	v_pk_add_f32 v[162:163], v[166:167], v[164:165]
	v_mul_f32_e32 v164, v112, v112
	v_mul_f32_e32 v165, v113, v113
	v_pk_add_f32 v[162:163], v[162:163], v[162:163] op_sel:[0,1] op_sel_hi:[1,0]
	v_mov_b32_e32 v159, v164
	v_mov_b32_e32 v163, v165
	v_pk_add_f32 v[158:159], v[158:159], v[162:163]
	v_mul_f32_e32 v162, v117, v117
	v_mul_f32_e32 v164, v119, v119
	v_mul_f32_e32 v166, v114, v114
	v_mul_f32_e32 v167, v115, v115
	v_pk_fma_f32 v[162:163], v[116:117], v[116:117], v[162:163] op_sel_hi:[1,1,0]
	v_pk_fma_f32 v[164:165], v[118:119], v[118:119], v[164:165] op_sel_hi:[1,1,0]
	v_mov_b32_e32 v163, v166
	v_mov_b32_e32 v165, v167
	v_pk_add_f32 v[162:163], v[162:163], v[164:165]
	v_mul_f32_e32 v151, v96, v96
	v_pk_add_f32 v[158:159], v[158:159], v[162:163]
	s_nop 0
	v_add_f32_e32 v158, v158, v159
	v_mbcnt_lo_u32_b32 v159, -1, 0
	v_mbcnt_hi_u32_b32 v159, -1, v159
	s_nop 0
	v_lshlrev_b32_e32 v159, 2, v159
	v_xor_b32_e32 v159, 64, v159
	ds_bpermute_b32 v159, v159, v158
	s_waitcnt lgkmcnt(0)
	v_add_f32_e32 v158, v158, v159
	v_mbcnt_lo_u32_b32 v159, -1, 0
	v_mbcnt_hi_u32_b32 v159, -1, v159
	s_nop 0
	v_lshlrev_b32_e32 v159, 2, v159
	v_xor_b32_e32 v159, 0x80, v159
	ds_bpermute_b32 v159, v159, v158
	s_waitcnt lgkmcnt(0)
	v_add_f32_e32 v158, v158, v159
	v_fmamk_f32 v158, v158, 0x3c800000, v208
	v_rsq_f32_e32 v162, v158
	v_mov_b64_e32 v[158:159], s[0:1]
	v_mad_i64_i32 v[164:165], s[0:1], v184, s71, v[158:159]
	v_pk_mul_f32 v[166:167], v[124:125], v[162:163] op_sel_hi:[1,0]
	v_pk_mul_f32 v[168:169], v[126:127], v[162:163] op_sel_hi:[1,0]
	v_pk_mul_f32 v[170:171], v[120:121], v[162:163] op_sel_hi:[1,0]
	v_pk_mul_f32 v[168:169], v[132:133], v[168:169]
	v_pk_mul_f32 v[166:167], v[134:135], v[166:167]
	v_pk_mul_f32 v[172:173], v[122:123], v[162:163] op_sel_hi:[1,0]
	v_pk_mul_f32 v[170:171], v[130:131], v[170:171]
	v_pk_mul_f32 v[172:173], v[128:129], v[172:173]
	v_cvt_pk_bf16_f32 v176, v166, v167
	v_cvt_pk_bf16_f32 v177, v168, v169
	v_cvt_pk_bf16_f32 v178, v170, v171
	v_pk_mul_f32 v[166:167], v[116:117], v[162:163] op_sel_hi:[1,0]
	v_pk_mul_f32 v[168:169], v[118:119], v[162:163] op_sel_hi:[1,0]
	v_pk_mul_f32 v[170:171], v[112:113], v[162:163] op_sel_hi:[1,0]
	v_pk_mul_f32 v[162:163], v[114:115], v[162:163] op_sel_hi:[1,0]
	v_lshl_add_u64 v[164:165], v[164:165], 0, v[174:175]
	v_cvt_pk_bf16_f32 v179, v172, v173
	v_pk_mul_f32 v[168:169], v[154:155], v[168:169]
	v_pk_mul_f32 v[166:167], v[156:157], v[166:167]
	v_pk_mul_f32 v[162:163], v[136:137], v[162:163]
	v_pk_mul_f32 v[170:171], v[152:153], v[170:171]
	global_store_dwordx4 v[164:165], v[176:179], off
	s_nop 1
	v_cvt_pk_bf16_f32 v176, v166, v167
	v_cvt_pk_bf16_f32 v177, v168, v169
	v_cvt_pk_bf16_f32 v178, v170, v171
	v_cvt_pk_bf16_f32 v179, v162, v163
	global_store_dwordx4 v[164:165], v[176:179], off offset:64
	v_pk_mul_f32 v[162:163], v[110:111], v[110:111]
	v_pk_mul_f32 v[164:165], v[108:109], v[108:109]
	s_nop 0
	v_pk_mov_b32 v[166:167], v[164:165], v[162:163] op_sel:[1,0]
	v_mov_b32_e32 v165, v163
	v_pk_add_f32 v[162:163], v[166:167], v[164:165]
	v_pk_mul_f32 v[164:165], v[106:107], v[106:107]
	v_pk_mul_f32 v[166:167], v[104:105], v[104:105]
	v_pk_add_f32 v[162:163], v[162:163], v[162:163] op_sel:[0,1] op_sel_hi:[1,0]
	v_pk_mov_b32 v[168:169], v[166:167], v[164:165] op_sel:[1,0]
	v_mov_b32_e32 v167, v165
	v_pk_add_f32 v[164:165], v[168:169], v[166:167]
	v_mul_f32_e32 v166, v97, v97
	v_pk_add_f32 v[164:165], v[164:165], v[164:165] op_sel:[0,1] op_sel_hi:[1,0]
	v_mov_b32_e32 v163, v151
	v_mov_b32_e32 v165, v166
	v_pk_add_f32 v[162:163], v[162:163], v[164:165]
	v_mul_f32_e32 v164, v101, v101
	v_mul_f32_e32 v167, v98, v98
	v_pk_fma_f32 v[164:165], v[100:101], v[100:101], v[164:165] op_sel_hi:[1,1,0]
	v_mul_f32_e32 v166, v103, v103
	v_mul_f32_e32 v168, v99, v99
	v_mov_b32_e32 v165, v167
	v_pk_fma_f32 v[166:167], v[102:103], v[102:103], v[166:167] op_sel_hi:[1,1,0]
	s_nop 0
	v_mov_b32_e32 v167, v168
	v_pk_add_f32 v[164:165], v[164:165], v[166:167]
	s_nop 0
	v_pk_add_f32 v[162:163], v[162:163], v[164:165]
	s_nop 0
	v_add_f32_e32 v151, v162, v163
	v_mbcnt_lo_u32_b32 v162, -1, 0
	v_mbcnt_hi_u32_b32 v162, -1, v162
	s_nop 0
	v_lshlrev_b32_e32 v162, 2, v162
	v_xor_b32_e32 v162, 64, v162
	ds_bpermute_b32 v162, v162, v151
	s_waitcnt lgkmcnt(0)
	v_add_f32_e32 v151, v151, v162
	v_mbcnt_lo_u32_b32 v162, -1, 0
	v_mbcnt_hi_u32_b32 v162, -1, v162
	s_nop 0
	v_lshlrev_b32_e32 v162, 2, v162
	v_xor_b32_e32 v162, 0x80, v162
	ds_bpermute_b32 v162, v162, v151
	s_waitcnt lgkmcnt(0)
	v_add_f32_e32 v151, v151, v162
	v_fmamk_f32 v151, v151, 0x3c800000, v208
	v_rsq_f32_e32 v162, v151
	v_add_u32_e32 v151, 16, v184
	v_mad_i64_i32 v[164:165], s[0:1], v151, s71, v[158:159]
	v_pk_mul_f32 v[166:167], v[108:109], v[162:163] op_sel_hi:[1,0]
	v_pk_mul_f32 v[168:169], v[110:111], v[162:163] op_sel_hi:[1,0]
	v_pk_mul_f32 v[170:171], v[104:105], v[162:163] op_sel_hi:[1,0]
	v_pk_mul_f32 v[168:169], v[132:133], v[168:169]
	v_pk_mul_f32 v[166:167], v[134:135], v[166:167]
	v_pk_mul_f32 v[172:173], v[106:107], v[162:163] op_sel_hi:[1,0]
	v_pk_mul_f32 v[170:171], v[130:131], v[170:171]
	v_pk_mul_f32 v[172:173], v[128:129], v[172:173]
	v_cvt_pk_bf16_f32 v176, v166, v167
	v_cvt_pk_bf16_f32 v177, v168, v169
	v_cvt_pk_bf16_f32 v178, v170, v171
	v_pk_mul_f32 v[166:167], v[100:101], v[162:163] op_sel_hi:[1,0]
	v_pk_mul_f32 v[168:169], v[102:103], v[162:163] op_sel_hi:[1,0]
	v_pk_mul_f32 v[170:171], v[96:97], v[162:163] op_sel_hi:[1,0]
	v_pk_mul_f32 v[162:163], v[98:99], v[162:163] op_sel_hi:[1,0]
	v_lshl_add_u64 v[164:165], v[164:165], 0, v[174:175]
	v_cvt_pk_bf16_f32 v179, v172, v173
	v_pk_mul_f32 v[168:169], v[154:155], v[168:169]
	v_pk_mul_f32 v[166:167], v[156:157], v[166:167]
	v_pk_mul_f32 v[162:163], v[136:137], v[162:163]
	v_pk_mul_f32 v[170:171], v[152:153], v[170:171]
	global_store_dwordx4 v[164:165], v[176:179], off
	v_mul_f32_e32 v151, v80, v80
	s_nop 0
	v_cvt_pk_bf16_f32 v176, v166, v167
	v_cvt_pk_bf16_f32 v177, v168, v169
	v_cvt_pk_bf16_f32 v178, v170, v171
	v_cvt_pk_bf16_f32 v179, v162, v163
	global_store_dwordx4 v[164:165], v[176:179], off offset:64
	v_pk_mul_f32 v[162:163], v[94:95], v[94:95]
	v_pk_mul_f32 v[164:165], v[92:93], v[92:93]
	s_nop 0
	v_pk_mov_b32 v[166:167], v[164:165], v[162:163] op_sel:[1,0]
	v_mov_b32_e32 v165, v163
	v_pk_add_f32 v[162:163], v[166:167], v[164:165]
	v_pk_mul_f32 v[164:165], v[90:91], v[90:91]
	v_pk_mul_f32 v[166:167], v[88:89], v[88:89]
	v_pk_add_f32 v[162:163], v[162:163], v[162:163] op_sel:[0,1] op_sel_hi:[1,0]
	v_pk_mov_b32 v[168:169], v[166:167], v[164:165] op_sel:[1,0]
	v_mov_b32_e32 v167, v165
	v_pk_add_f32 v[164:165], v[168:169], v[166:167]
	v_mul_f32_e32 v166, v81, v81
	v_pk_add_f32 v[164:165], v[164:165], v[164:165] op_sel:[0,1] op_sel_hi:[1,0]
	v_mov_b32_e32 v163, v151
	v_mov_b32_e32 v165, v166
	v_pk_add_f32 v[162:163], v[162:163], v[164:165]
	v_mul_f32_e32 v164, v85, v85
	v_mul_f32_e32 v167, v82, v82
	v_pk_fma_f32 v[164:165], v[84:85], v[84:85], v[164:165] op_sel_hi:[1,1,0]
	v_mul_f32_e32 v166, v87, v87
	v_mul_f32_e32 v168, v83, v83
	v_mov_b32_e32 v165, v167
	v_pk_fma_f32 v[166:167], v[86:87], v[86:87], v[166:167] op_sel_hi:[1,1,0]
	s_nop 0
	v_mov_b32_e32 v167, v168
	v_pk_add_f32 v[164:165], v[164:165], v[166:167]
	s_nop 0
	v_pk_add_f32 v[162:163], v[162:163], v[164:165]
	s_nop 0
	v_add_f32_e32 v151, v162, v163
	v_mbcnt_lo_u32_b32 v162, -1, 0
	v_mbcnt_hi_u32_b32 v162, -1, v162
	s_nop 0
	v_lshlrev_b32_e32 v162, 2, v162
	v_xor_b32_e32 v162, 64, v162
	ds_bpermute_b32 v162, v162, v151
	s_waitcnt lgkmcnt(0)
	v_add_f32_e32 v151, v151, v162
	v_mbcnt_lo_u32_b32 v162, -1, 0
	v_mbcnt_hi_u32_b32 v162, -1, v162
	s_nop 0
	v_lshlrev_b32_e32 v162, 2, v162
	v_xor_b32_e32 v162, 0x80, v162
	ds_bpermute_b32 v162, v162, v151
	s_waitcnt lgkmcnt(0)
	v_add_f32_e32 v151, v151, v162
	v_fmamk_f32 v151, v151, 0x3c800000, v208
	v_rsq_f32_e32 v162, v151
	v_add_u32_e32 v151, 32, v184
	v_mad_i64_i32 v[164:165], s[0:1], v151, s71, v[158:159]
	v_pk_mul_f32 v[166:167], v[92:93], v[162:163] op_sel_hi:[1,0]
	v_pk_mul_f32 v[168:169], v[94:95], v[162:163] op_sel_hi:[1,0]
	v_pk_mul_f32 v[170:171], v[88:89], v[162:163] op_sel_hi:[1,0]
	v_pk_mul_f32 v[168:169], v[132:133], v[168:169]
	v_pk_mul_f32 v[166:167], v[134:135], v[166:167]
	v_pk_mul_f32 v[172:173], v[90:91], v[162:163] op_sel_hi:[1,0]
	v_pk_mul_f32 v[170:171], v[130:131], v[170:171]
	v_pk_mul_f32 v[172:173], v[128:129], v[172:173]
	v_cvt_pk_bf16_f32 v176, v166, v167
	v_cvt_pk_bf16_f32 v177, v168, v169
	v_cvt_pk_bf16_f32 v178, v170, v171
	v_pk_mul_f32 v[166:167], v[84:85], v[162:163] op_sel_hi:[1,0]
	v_pk_mul_f32 v[168:169], v[86:87], v[162:163] op_sel_hi:[1,0]
	v_pk_mul_f32 v[170:171], v[80:81], v[162:163] op_sel_hi:[1,0]
	v_pk_mul_f32 v[162:163], v[82:83], v[162:163] op_sel_hi:[1,0]
	v_lshl_add_u64 v[164:165], v[164:165], 0, v[174:175]
	v_cvt_pk_bf16_f32 v179, v172, v173
	v_pk_mul_f32 v[168:169], v[154:155], v[168:169]
	v_pk_mul_f32 v[166:167], v[156:157], v[166:167]
	v_pk_mul_f32 v[162:163], v[136:137], v[162:163]
	v_pk_mul_f32 v[170:171], v[152:153], v[170:171]
	global_store_dwordx4 v[164:165], v[176:179], off
	v_mul_f32_e32 v151, v64, v64
	s_nop 0
	v_cvt_pk_bf16_f32 v176, v166, v167
	v_cvt_pk_bf16_f32 v177, v168, v169
	v_cvt_pk_bf16_f32 v178, v170, v171
	v_cvt_pk_bf16_f32 v179, v162, v163
	global_store_dwordx4 v[164:165], v[176:179], off offset:64
	v_pk_mul_f32 v[162:163], v[78:79], v[78:79]
	v_pk_mul_f32 v[164:165], v[76:77], v[76:77]
	s_nop 0
	v_pk_mov_b32 v[166:167], v[164:165], v[162:163] op_sel:[1,0]
	v_mov_b32_e32 v165, v163
	v_pk_add_f32 v[162:163], v[166:167], v[164:165]
	v_pk_mul_f32 v[164:165], v[74:75], v[74:75]
	v_pk_mul_f32 v[166:167], v[72:73], v[72:73]
	v_pk_add_f32 v[162:163], v[162:163], v[162:163] op_sel:[0,1] op_sel_hi:[1,0]
	v_pk_mov_b32 v[168:169], v[166:167], v[164:165] op_sel:[1,0]
	v_mov_b32_e32 v167, v165
	v_pk_add_f32 v[164:165], v[168:169], v[166:167]
	v_mul_f32_e32 v166, v65, v65
	v_pk_add_f32 v[164:165], v[164:165], v[164:165] op_sel:[0,1] op_sel_hi:[1,0]
	v_mov_b32_e32 v163, v151
	v_mov_b32_e32 v165, v166
	v_pk_add_f32 v[162:163], v[162:163], v[164:165]
	v_mul_f32_e32 v164, v69, v69
	v_mul_f32_e32 v167, v66, v66
	v_pk_fma_f32 v[164:165], v[68:69], v[68:69], v[164:165] op_sel_hi:[1,1,0]
	v_mul_f32_e32 v166, v71, v71
	v_mul_f32_e32 v168, v67, v67
	v_mov_b32_e32 v165, v167
	v_pk_fma_f32 v[166:167], v[70:71], v[70:71], v[166:167] op_sel_hi:[1,1,0]
	s_nop 0
	v_mov_b32_e32 v167, v168
	v_pk_add_f32 v[164:165], v[164:165], v[166:167]
	s_nop 0
	v_pk_add_f32 v[162:163], v[162:163], v[164:165]
	s_nop 0
	v_add_f32_e32 v151, v162, v163
	v_mbcnt_lo_u32_b32 v162, -1, 0
	v_mbcnt_hi_u32_b32 v162, -1, v162
	s_nop 0
	v_lshlrev_b32_e32 v162, 2, v162
	v_xor_b32_e32 v162, 64, v162
	ds_bpermute_b32 v162, v162, v151
	s_waitcnt lgkmcnt(0)
	v_add_f32_e32 v151, v151, v162
	v_mbcnt_lo_u32_b32 v162, -1, 0
	v_mbcnt_hi_u32_b32 v162, -1, v162
	s_nop 0
	v_lshlrev_b32_e32 v162, 2, v162
	v_xor_b32_e32 v162, 0x80, v162
	ds_bpermute_b32 v162, v162, v151
	s_waitcnt lgkmcnt(0)
	v_add_f32_e32 v151, v151, v162
	v_fmamk_f32 v151, v151, 0x3c800000, v208
	v_rsq_f32_e32 v162, v151
	v_add_u32_e32 v151, 48, v184
	v_mad_i64_i32 v[164:165], s[0:1], v151, s71, v[158:159]
	v_pk_mul_f32 v[166:167], v[76:77], v[162:163] op_sel_hi:[1,0]
	v_pk_mul_f32 v[168:169], v[78:79], v[162:163] op_sel_hi:[1,0]
	v_pk_mul_f32 v[170:171], v[72:73], v[162:163] op_sel_hi:[1,0]
	v_pk_mul_f32 v[168:169], v[132:133], v[168:169]
	v_pk_mul_f32 v[166:167], v[134:135], v[166:167]
	v_pk_mul_f32 v[172:173], v[74:75], v[162:163] op_sel_hi:[1,0]
	v_pk_mul_f32 v[170:171], v[130:131], v[170:171]
	v_pk_mul_f32 v[172:173], v[128:129], v[172:173]
	v_cvt_pk_bf16_f32 v176, v166, v167
	v_cvt_pk_bf16_f32 v177, v168, v169
	v_cvt_pk_bf16_f32 v178, v170, v171
	v_pk_mul_f32 v[166:167], v[68:69], v[162:163] op_sel_hi:[1,0]
	v_pk_mul_f32 v[168:169], v[70:71], v[162:163] op_sel_hi:[1,0]
	v_pk_mul_f32 v[170:171], v[64:65], v[162:163] op_sel_hi:[1,0]
	v_pk_mul_f32 v[162:163], v[66:67], v[162:163] op_sel_hi:[1,0]
	v_lshl_add_u64 v[164:165], v[164:165], 0, v[174:175]
	v_cvt_pk_bf16_f32 v179, v172, v173
	v_pk_mul_f32 v[168:169], v[154:155], v[168:169]
	v_pk_mul_f32 v[166:167], v[156:157], v[166:167]
	v_pk_mul_f32 v[162:163], v[136:137], v[162:163]
	v_pk_mul_f32 v[170:171], v[152:153], v[170:171]
	global_store_dwordx4 v[164:165], v[176:179], off
	v_add_u32_e32 v151, 0x80, v184
	s_nop 0
	v_cvt_pk_bf16_f32 v176, v166, v167
	v_cvt_pk_bf16_f32 v177, v168, v169
	v_cvt_pk_bf16_f32 v178, v170, v171
	v_cvt_pk_bf16_f32 v179, v162, v163
	global_store_dwordx4 v[164:165], v[176:179], off offset:64
	v_pk_mul_f32 v[162:163], v[62:63], v[62:63]
	v_pk_mul_f32 v[164:165], v[60:61], v[60:61]
	s_nop 0
	v_pk_mov_b32 v[166:167], v[164:165], v[162:163] op_sel:[1,0]
	v_mov_b32_e32 v165, v163
	v_pk_add_f32 v[162:163], v[166:167], v[164:165]
	v_pk_mul_f32 v[164:165], v[58:59], v[58:59]
	v_pk_mul_f32 v[166:167], v[56:57], v[56:57]
	v_pk_add_f32 v[162:163], v[162:163], v[162:163] op_sel:[0,1] op_sel_hi:[1,0]
	v_pk_mov_b32 v[168:169], v[166:167], v[164:165] op_sel:[1,0]
	v_mov_b32_e32 v167, v165
	v_pk_add_f32 v[164:165], v[168:169], v[166:167]
	v_mul_f32_e32 v166, v48, v48
	v_mul_f32_e32 v167, v49, v49
	v_pk_add_f32 v[164:165], v[164:165], v[164:165] op_sel:[0,1] op_sel_hi:[1,0]
	v_mov_b32_e32 v163, v166
	v_mov_b32_e32 v165, v167
	v_pk_add_f32 v[162:163], v[162:163], v[164:165]
	v_mul_f32_e32 v164, v53, v53
	v_mul_f32_e32 v166, v55, v55
	v_mul_f32_e32 v168, v50, v50
	v_mul_f32_e32 v169, v51, v51
	v_pk_fma_f32 v[164:165], v[52:53], v[52:53], v[164:165] op_sel_hi:[1,1,0]
	v_pk_fma_f32 v[166:167], v[54:55], v[54:55], v[166:167] op_sel_hi:[1,1,0]
	v_mov_b32_e32 v165, v168
	v_mov_b32_e32 v167, v169
	v_pk_add_f32 v[164:165], v[164:165], v[166:167]
	s_nop 0
	v_pk_add_f32 v[162:163], v[162:163], v[164:165]
	v_mad_i64_i32 v[164:165], s[0:1], v151, s71, v[158:159]
	v_add_f32_e32 v162, v162, v163
	v_mbcnt_lo_u32_b32 v163, -1, 0
	v_mbcnt_hi_u32_b32 v163, -1, v163
	v_lshl_add_u64 v[164:165], v[164:165], 0, v[174:175]
	v_lshlrev_b32_e32 v163, 2, v163
	v_xor_b32_e32 v163, 64, v163
	ds_bpermute_b32 v163, v163, v162
	v_mul_f32_e32 v151, v32, v32
	s_waitcnt lgkmcnt(0)
	v_add_f32_e32 v162, v162, v163
	v_mbcnt_lo_u32_b32 v163, -1, 0
	v_mbcnt_hi_u32_b32 v163, -1, v163
	s_nop 0
	v_lshlrev_b32_e32 v163, 2, v163
	v_xor_b32_e32 v163, 0x80, v163
	ds_bpermute_b32 v163, v163, v162
	s_waitcnt lgkmcnt(0)
	v_add_f32_e32 v162, v162, v163
	v_fmamk_f32 v162, v162, 0x3c800000, v208
	v_rsq_f32_e32 v162, v162
	s_nop 0
	v_pk_mul_f32 v[166:167], v[60:61], v[162:163] op_sel_hi:[1,0]
	v_pk_mul_f32 v[168:169], v[62:63], v[162:163] op_sel_hi:[1,0]
	v_pk_mul_f32 v[170:171], v[56:57], v[162:163] op_sel_hi:[1,0]
	v_pk_mul_f32 v[168:169], v[132:133], v[168:169]
	v_pk_mul_f32 v[166:167], v[134:135], v[166:167]
	v_pk_mul_f32 v[172:173], v[58:59], v[162:163] op_sel_hi:[1,0]
	v_pk_mul_f32 v[170:171], v[130:131], v[170:171]
	v_pk_mul_f32 v[172:173], v[128:129], v[172:173]
	v_cvt_pk_bf16_f32 v176, v166, v167
	v_cvt_pk_bf16_f32 v177, v168, v169
	v_cvt_pk_bf16_f32 v178, v170, v171
	v_pk_mul_f32 v[166:167], v[52:53], v[162:163] op_sel_hi:[1,0]
	v_pk_mul_f32 v[168:169], v[54:55], v[162:163] op_sel_hi:[1,0]
	v_pk_mul_f32 v[170:171], v[48:49], v[162:163] op_sel_hi:[1,0]
	v_pk_mul_f32 v[162:163], v[50:51], v[162:163] op_sel_hi:[1,0]
	v_cvt_pk_bf16_f32 v179, v172, v173
	v_pk_mul_f32 v[168:169], v[154:155], v[168:169]
	v_pk_mul_f32 v[166:167], v[156:157], v[166:167]
	v_pk_mul_f32 v[162:163], v[136:137], v[162:163]
	v_pk_mul_f32 v[170:171], v[152:153], v[170:171]
	global_store_dwordx4 v[164:165], v[176:179], off
	s_nop 1
	v_cvt_pk_bf16_f32 v176, v166, v167
	v_cvt_pk_bf16_f32 v177, v168, v169
	v_cvt_pk_bf16_f32 v178, v170, v171
	v_cvt_pk_bf16_f32 v179, v162, v163
	global_store_dwordx4 v[164:165], v[176:179], off offset:64
	v_pk_mul_f32 v[162:163], v[46:47], v[46:47]
	v_pk_mul_f32 v[164:165], v[44:45], v[44:45]
	s_nop 0
	v_pk_mov_b32 v[166:167], v[164:165], v[162:163] op_sel:[1,0]
	v_mov_b32_e32 v165, v163
	v_pk_add_f32 v[162:163], v[166:167], v[164:165]
	v_pk_mul_f32 v[164:165], v[42:43], v[42:43]
	v_pk_mul_f32 v[166:167], v[40:41], v[40:41]
	v_pk_add_f32 v[162:163], v[162:163], v[162:163] op_sel:[0,1] op_sel_hi:[1,0]
	v_pk_mov_b32 v[168:169], v[166:167], v[164:165] op_sel:[1,0]
	v_mov_b32_e32 v167, v165
	v_pk_add_f32 v[164:165], v[168:169], v[166:167]
	v_mul_f32_e32 v166, v33, v33
	v_pk_add_f32 v[164:165], v[164:165], v[164:165] op_sel:[0,1] op_sel_hi:[1,0]
	v_mov_b32_e32 v163, v151
	v_mov_b32_e32 v165, v166
	v_pk_add_f32 v[162:163], v[162:163], v[164:165]
	v_mul_f32_e32 v164, v37, v37
	v_mul_f32_e32 v167, v34, v34
	v_pk_fma_f32 v[164:165], v[36:37], v[36:37], v[164:165] op_sel_hi:[1,1,0]
	v_mul_f32_e32 v166, v39, v39
	v_mul_f32_e32 v168, v35, v35
	v_mov_b32_e32 v165, v167
	v_pk_fma_f32 v[166:167], v[38:39], v[38:39], v[166:167] op_sel_hi:[1,1,0]
	s_nop 0
	v_mov_b32_e32 v167, v168
	v_pk_add_f32 v[164:165], v[164:165], v[166:167]
	s_nop 0
	v_pk_add_f32 v[162:163], v[162:163], v[164:165]
	s_nop 0
	v_add_f32_e32 v151, v162, v163
	v_mbcnt_lo_u32_b32 v162, -1, 0
	v_mbcnt_hi_u32_b32 v162, -1, v162
	s_nop 0
	v_lshlrev_b32_e32 v162, 2, v162
	v_xor_b32_e32 v162, 64, v162
	ds_bpermute_b32 v162, v162, v151
	s_waitcnt lgkmcnt(0)
	v_add_f32_e32 v151, v151, v162
	v_mbcnt_lo_u32_b32 v162, -1, 0
	v_mbcnt_hi_u32_b32 v162, -1, v162
	s_nop 0
	v_lshlrev_b32_e32 v162, 2, v162
	v_xor_b32_e32 v162, 0x80, v162
	ds_bpermute_b32 v162, v162, v151
	s_waitcnt lgkmcnt(0)
	v_add_f32_e32 v151, v151, v162
	v_fmamk_f32 v151, v151, 0x3c800000, v208
	v_rsq_f32_e32 v162, v151
	v_add_u32_e32 v151, 0x90, v184
	v_mad_i64_i32 v[164:165], s[0:1], v151, s71, v[158:159]
	v_pk_mul_f32 v[166:167], v[44:45], v[162:163] op_sel_hi:[1,0]
	v_pk_mul_f32 v[168:169], v[46:47], v[162:163] op_sel_hi:[1,0]
	v_pk_mul_f32 v[170:171], v[40:41], v[162:163] op_sel_hi:[1,0]
	v_pk_mul_f32 v[168:169], v[132:133], v[168:169]
	v_pk_mul_f32 v[166:167], v[134:135], v[166:167]
	v_pk_mul_f32 v[172:173], v[42:43], v[162:163] op_sel_hi:[1,0]
	v_pk_mul_f32 v[170:171], v[130:131], v[170:171]
	v_pk_mul_f32 v[172:173], v[128:129], v[172:173]
	v_cvt_pk_bf16_f32 v176, v166, v167
	v_cvt_pk_bf16_f32 v177, v168, v169
	v_cvt_pk_bf16_f32 v178, v170, v171
	v_pk_mul_f32 v[166:167], v[36:37], v[162:163] op_sel_hi:[1,0]
	v_pk_mul_f32 v[168:169], v[38:39], v[162:163] op_sel_hi:[1,0]
	v_pk_mul_f32 v[170:171], v[32:33], v[162:163] op_sel_hi:[1,0]
	v_pk_mul_f32 v[162:163], v[34:35], v[162:163] op_sel_hi:[1,0]
	v_lshl_add_u64 v[164:165], v[164:165], 0, v[174:175]
	v_cvt_pk_bf16_f32 v179, v172, v173
	v_pk_mul_f32 v[168:169], v[154:155], v[168:169]
	v_pk_mul_f32 v[166:167], v[156:157], v[166:167]
	v_pk_mul_f32 v[162:163], v[136:137], v[162:163]
	v_pk_mul_f32 v[170:171], v[152:153], v[170:171]
	global_store_dwordx4 v[164:165], v[176:179], off
	v_mul_f32_e32 v151, v16, v16
	s_nop 0
	v_cvt_pk_bf16_f32 v176, v166, v167
	v_cvt_pk_bf16_f32 v177, v168, v169
	v_cvt_pk_bf16_f32 v178, v170, v171
	v_cvt_pk_bf16_f32 v179, v162, v163
	global_store_dwordx4 v[164:165], v[176:179], off offset:64
	v_pk_mul_f32 v[162:163], v[30:31], v[30:31]
	v_pk_mul_f32 v[164:165], v[28:29], v[28:29]
	s_nop 0
	v_pk_mov_b32 v[166:167], v[164:165], v[162:163] op_sel:[1,0]
	v_mov_b32_e32 v165, v163
	v_pk_add_f32 v[162:163], v[166:167], v[164:165]
	v_pk_mul_f32 v[164:165], v[26:27], v[26:27]
	v_pk_mul_f32 v[166:167], v[24:25], v[24:25]
	v_pk_add_f32 v[162:163], v[162:163], v[162:163] op_sel:[0,1] op_sel_hi:[1,0]
	v_pk_mov_b32 v[168:169], v[166:167], v[164:165] op_sel:[1,0]
	v_mov_b32_e32 v167, v165
	v_pk_add_f32 v[164:165], v[168:169], v[166:167]
	v_mul_f32_e32 v166, v17, v17
	v_pk_add_f32 v[164:165], v[164:165], v[164:165] op_sel:[0,1] op_sel_hi:[1,0]
	v_mov_b32_e32 v163, v151
	v_mov_b32_e32 v165, v166
	v_pk_add_f32 v[162:163], v[162:163], v[164:165]
	v_mul_f32_e32 v164, v21, v21
	v_mul_f32_e32 v167, v18, v18
	v_pk_fma_f32 v[164:165], v[20:21], v[20:21], v[164:165] op_sel_hi:[1,1,0]
	v_mul_f32_e32 v166, v23, v23
	v_mul_f32_e32 v168, v19, v19
	v_mov_b32_e32 v165, v167
	v_pk_fma_f32 v[166:167], v[22:23], v[22:23], v[166:167] op_sel_hi:[1,1,0]
	s_nop 0
	v_mov_b32_e32 v167, v168
	v_pk_add_f32 v[164:165], v[164:165], v[166:167]
	s_nop 0
	v_pk_add_f32 v[162:163], v[162:163], v[164:165]
	s_nop 0
	v_add_f32_e32 v151, v162, v163
	v_mbcnt_lo_u32_b32 v162, -1, 0
	v_mbcnt_hi_u32_b32 v162, -1, v162
	s_nop 0
	v_lshlrev_b32_e32 v162, 2, v162
	v_xor_b32_e32 v162, 64, v162
	ds_bpermute_b32 v162, v162, v151
	s_waitcnt lgkmcnt(0)
	v_add_f32_e32 v151, v151, v162
	v_mbcnt_lo_u32_b32 v162, -1, 0
	v_mbcnt_hi_u32_b32 v162, -1, v162
	s_nop 0
	v_lshlrev_b32_e32 v162, 2, v162
	v_xor_b32_e32 v162, 0x80, v162
	ds_bpermute_b32 v162, v162, v151
	s_waitcnt lgkmcnt(0)
	v_add_f32_e32 v151, v151, v162
	v_fmamk_f32 v151, v151, 0x3c800000, v208
	v_rsq_f32_e32 v162, v151
	v_add_u32_e32 v151, 0xa0, v184
	v_mad_i64_i32 v[164:165], s[0:1], v151, s71, v[158:159]
	v_pk_mul_f32 v[166:167], v[28:29], v[162:163] op_sel_hi:[1,0]
	v_pk_mul_f32 v[168:169], v[30:31], v[162:163] op_sel_hi:[1,0]
	v_pk_mul_f32 v[170:171], v[24:25], v[162:163] op_sel_hi:[1,0]
	v_pk_mul_f32 v[168:169], v[132:133], v[168:169]
	v_pk_mul_f32 v[166:167], v[134:135], v[166:167]
	v_pk_mul_f32 v[172:173], v[26:27], v[162:163] op_sel_hi:[1,0]
	v_pk_mul_f32 v[170:171], v[130:131], v[170:171]
	v_pk_mul_f32 v[172:173], v[128:129], v[172:173]
	v_cvt_pk_bf16_f32 v176, v166, v167
	v_cvt_pk_bf16_f32 v177, v168, v169
	v_cvt_pk_bf16_f32 v178, v170, v171
	v_pk_mul_f32 v[166:167], v[20:21], v[162:163] op_sel_hi:[1,0]
	v_pk_mul_f32 v[168:169], v[22:23], v[162:163] op_sel_hi:[1,0]
	v_pk_mul_f32 v[170:171], v[16:17], v[162:163] op_sel_hi:[1,0]
	v_pk_mul_f32 v[162:163], v[18:19], v[162:163] op_sel_hi:[1,0]
	v_lshl_add_u64 v[164:165], v[164:165], 0, v[174:175]
	v_cvt_pk_bf16_f32 v179, v172, v173
	v_pk_mul_f32 v[168:169], v[154:155], v[168:169]
	v_pk_mul_f32 v[166:167], v[156:157], v[166:167]
	v_pk_mul_f32 v[162:163], v[136:137], v[162:163]
	v_pk_mul_f32 v[170:171], v[152:153], v[170:171]
	global_store_dwordx4 v[164:165], v[176:179], off
	v_mul_f32_e32 v151, v0, v0
	s_nop 0
	v_cvt_pk_bf16_f32 v176, v166, v167
	v_cvt_pk_bf16_f32 v177, v168, v169
	v_cvt_pk_bf16_f32 v178, v170, v171
	v_cvt_pk_bf16_f32 v179, v162, v163
	global_store_dwordx4 v[164:165], v[176:179], off offset:64
	v_pk_mul_f32 v[162:163], v[14:15], v[14:15]
	v_pk_mul_f32 v[164:165], v[12:13], v[12:13]
	s_nop 0
	v_pk_mov_b32 v[166:167], v[164:165], v[162:163] op_sel:[1,0]
	v_mov_b32_e32 v165, v163
	v_pk_add_f32 v[162:163], v[166:167], v[164:165]
	v_pk_mul_f32 v[164:165], v[10:11], v[10:11]
	v_pk_mul_f32 v[166:167], v[8:9], v[8:9]
	v_pk_add_f32 v[162:163], v[162:163], v[162:163] op_sel:[0,1] op_sel_hi:[1,0]
	v_pk_mov_b32 v[168:169], v[166:167], v[164:165] op_sel:[1,0]
	v_mov_b32_e32 v167, v165
	v_pk_add_f32 v[164:165], v[168:169], v[166:167]
	v_mul_f32_e32 v166, v1, v1
	v_pk_add_f32 v[164:165], v[164:165], v[164:165] op_sel:[0,1] op_sel_hi:[1,0]
	v_mov_b32_e32 v163, v151
	v_mov_b32_e32 v165, v166
	v_pk_add_f32 v[162:163], v[162:163], v[164:165]
	v_mul_f32_e32 v164, v5, v5
	v_mul_f32_e32 v167, v2, v2
	v_pk_fma_f32 v[164:165], v[4:5], v[4:5], v[164:165] op_sel_hi:[1,1,0]
	v_mul_f32_e32 v166, v7, v7
	v_mul_f32_e32 v168, v3, v3
	v_mov_b32_e32 v165, v167
	v_pk_fma_f32 v[166:167], v[6:7], v[6:7], v[166:167] op_sel_hi:[1,1,0]
	s_nop 0
	v_mov_b32_e32 v167, v168
	v_pk_add_f32 v[164:165], v[164:165], v[166:167]
	s_nop 0
	v_pk_add_f32 v[162:163], v[162:163], v[164:165]
	s_nop 0
	v_add_f32_e32 v151, v162, v163
	v_mbcnt_lo_u32_b32 v162, -1, 0
	v_mbcnt_hi_u32_b32 v162, -1, v162
	s_nop 0
	v_lshlrev_b32_e32 v162, 2, v162
	v_xor_b32_e32 v162, 64, v162
	ds_bpermute_b32 v162, v162, v151
	s_waitcnt lgkmcnt(0)
	v_add_f32_e32 v151, v151, v162
	v_mbcnt_lo_u32_b32 v162, -1, 0
	v_mbcnt_hi_u32_b32 v162, -1, v162
	s_nop 0
	v_lshlrev_b32_e32 v162, 2, v162
	v_xor_b32_e32 v162, 0x80, v162
	ds_bpermute_b32 v162, v162, v151
	s_waitcnt lgkmcnt(0)
	v_add_f32_e32 v151, v151, v162
	v_fmamk_f32 v151, v151, 0x3c800000, v208
	v_rsq_f32_e32 v162, v151
	v_add_u32_e32 v151, 0xb0, v184
	v_mad_i64_i32 v[158:159], s[0:1], v151, s71, v[158:159]
	v_pk_mul_f32 v[164:165], v[12:13], v[162:163] op_sel_hi:[1,0]
	v_pk_mul_f32 v[166:167], v[14:15], v[162:163] op_sel_hi:[1,0]
	v_pk_mul_f32 v[134:135], v[134:135], v[164:165]
	v_pk_mul_f32 v[132:133], v[132:133], v[166:167]
	v_pk_mul_f32 v[164:165], v[8:9], v[162:163] op_sel_hi:[1,0]
	v_pk_mul_f32 v[166:167], v[10:11], v[162:163] op_sel_hi:[1,0]
	v_pk_mul_f32 v[130:131], v[130:131], v[164:165]
	v_pk_mul_f32 v[166:167], v[128:129], v[166:167]
	v_lshl_add_u64 v[158:159], v[158:159], 0, v[174:175]
	v_cvt_pk_bf16_f32 v128, v134, v135
	v_cvt_pk_bf16_f32 v129, v132, v133
	v_cvt_pk_bf16_f32 v130, v130, v131
	v_cvt_pk_bf16_f32 v131, v166, v167
	global_store_dwordx4 v[158:159], v[128:131], off
	v_pk_mul_f32 v[132:133], v[0:1], v[162:163] op_sel_hi:[1,0]
	v_pk_mul_f32 v[134:135], v[2:3], v[162:163] op_sel_hi:[1,0]
	v_pk_mul_f32 v[128:129], v[4:5], v[162:163] op_sel_hi:[1,0]
	v_pk_mul_f32 v[130:131], v[6:7], v[162:163] op_sel_hi:[1,0]
	v_pk_mul_f32 v[128:129], v[156:157], v[128:129]
	v_pk_mul_f32 v[130:131], v[154:155], v[130:131]
	v_pk_mul_f32 v[134:135], v[136:137], v[134:135]
	v_pk_mul_f32 v[132:133], v[152:153], v[132:133]
	v_cvt_pk_bf16_f32 v128, v128, v129
	v_cvt_pk_bf16_f32 v129, v130, v131
	v_cvt_pk_bf16_f32 v130, v132, v133
	v_cvt_pk_bf16_f32 v131, v134, v135
	global_store_dwordx4 v[158:159], v[128:131], off offset:64
